# speedup vs baseline: 1.0282x; 1.0031x over previous
;     __device__ __forceinline__ void fused(f32x4 (&acc)[2][2][4][2], const Unit& u, int wr, int wc, int fr, int fq, LAS unsigned char* lds) const {
;     ...
;         if (tid < 256) { float S = 0.f, Q = 0.f;
; #pragma unroll
;             for (int t = 0; t < 8; ++t) { const unsigned long long w = __hip_atomic_load(slot + t, __ATOMIC_RELAXED, __HIP_MEMORY_SCOPE_AGENT); S += __uint_as_float((unsigned)w); Q += __uint_as_float((unsigned)(w >> 32)); }
;             const float mean = S * (1.0f / 2048.0f), var = Q * (1.0f / 2048.0f) - mean * mean;
;             S2[tid * 2] = mean; S2[tid * 2 + 1] = rsqrtf(fmaxf(var, 0.f) + LN_EPS); }
.LBB0_577:
	s_or_b64 exec, exec, s[2:3]
	s_waitcnt vmcnt(0) lgkmcnt(0)
	s_barrier
	v_ashrrev_i32_e32 v139, 31, v138
	v_mad_i64_i32 v[198:199], s[2:3], v138, s93, 0
	v_ashrrev_i32_e32 v143, 31, v142
	v_mad_i64_i32 v[196:197], s[2:3], v142, s93, 0
	v_ashrrev_i32_e32 v147, 31, v146
	v_mad_i64_i32 v[194:195], s[2:3], v146, s93, 0
	v_ashrrev_i32_e32 v151, 31, v150
	v_mad_i64_i32 v[192:193], s[2:3], v150, s93, 0
	v_ashrrev_i32_e32 v155, 31, v154
	v_mad_i64_i32 v[190:191], s[2:3], v154, s93, 0
	v_ashrrev_i32_e32 v159, 31, v158
	v_mad_i64_i32 v[188:189], s[2:3], v158, s93, 0
	v_ashrrev_i32_e32 v165, 31, v164
	v_mad_i64_i32 v[186:187], s[2:3], v164, s93, 0
	v_ashrrev_i32_e32 v175, 31, v174
	v_mad_i64_i32 v[184:185], s[2:3], v174, s93, 0
	v_lshlrev_b32_e32 v2, 3, v246
	s_and_saveexec_b64 s[10:11], s[0:1]
	s_cbranch_execz .LBB0_579
	global_load_dwordx2 v[4:5], v[0:1], off sc1
	global_load_dwordx2 v[6:7], v[0:1], off offset:8 sc1
	global_load_dwordx2 v[8:9], v[0:1], off offset:16 sc1
	global_load_dwordx2 v[10:11], v[0:1], off offset:24 sc1
	global_load_dwordx2 v[208:209], v[0:1], off offset:32 sc1
	global_load_dwordx2 v[210:211], v[0:1], off offset:40 sc1
	global_load_dwordx2 v[212:213], v[0:1], off offset:48 sc1
	global_load_dwordx2 v[214:215], v[0:1], off offset:56 sc1
	s_mov_b32 s0, 0x3a000000
	v_add_u32_e32 v2, 0, v2
	v_add_u32_e32 v2, 0x22040, v2
	s_waitcnt vmcnt(0) lgkmcnt(0)
	v_add_f32_e32 v3, 0, v4
	v_add_f32_e32 v5, 0, v5
	v_add_f32_e32 v3, v3, v6
	v_add_f32_e32 v5, v5, v7
	v_add_f32_e32 v3, v3, v8
	v_add_f32_e32 v5, v5, v9
	v_add_f32_e32 v3, v3, v10
	v_add_f32_e32 v5, v5, v11
	v_add_f32_e32 v3, v3, v208
	v_add_f32_e32 v5, v5, v209
	v_add_f32_e32 v3, v3, v210
	v_add_f32_e32 v5, v5, v211
	v_add_f32_e32 v3, v3, v212
	v_add_f32_e32 v4, v5, v213
	v_add_f32_e32 v0, v3, v214
	v_mul_f32_e32 v0, 0x3a000000, v0
	v_add_f32_e32 v1, v4, v215
	v_mul_f32_e32 v3, v0, v0
	v_fma_f32 v1, v1, s0, -v3
	v_max_f32_e32 v1, 0, v1
	v_add_f32_e32 v1, 0x3727c5ac, v1
	s_mov_b32 s0, 0x800000
	v_cmp_gt_f32_e32 vcc, s0, v1
	v_mul_f32_e32 v3, 0x4b800000, v1
	s_nop 0
	v_cndmask_b32_e32 v1, v1, v3, vcc
	v_rsq_f32_e32 v1, v1
	s_nop 0
	v_mul_f32_e32 v3, 0x45800000, v1
	v_cndmask_b32_e32 v1, v1, v3, vcc
	ds_write_b64 v2, v[0:1]
